# v068 + removed s_sleep 1 from the 30 grid-barrier spin loops (faster wake-up after release)
# baseline (speedup 1.0000x reference)
.LBB0_232:
	global_load_dword v15, v16, s[6:7] sc1
	s_waitcnt lgkmcnt(0)
	global_load_dword v0, v16, s[8:9] sc1
	global_load_dword v1, v16, s[10:11] sc1
	global_load_dword v2, v16, s[14:15] sc1
	global_load_dword v3, v16, s[16:17] sc1
	global_load_dword v4, v16, s[18:19] sc1
	global_load_dword v5, v16, s[54:55] sc1
	global_load_dword v6, v16, s[56:57] sc1
	global_load_dword v7, v16, s[58:59] sc1
	global_load_dword v8, v16, s[64:65] sc1
	global_load_dword v9, v16, s[70:71] sc1
	global_load_dword v10, v16, s[72:73] sc1
	global_load_dword v11, v16, s[74:75] sc1
	global_load_dword v12, v16, s[76:77] sc1
	global_load_dword v13, v16, s[78:79] sc1
	global_load_dword v14, v16, s[80:81] sc1
	s_mov_b64 s[20:21], -1
	s_mov_b64 s[82:83], -1
	s_waitcnt vmcnt(14)
	v_add_u32_e32 v17, v0, v15
	s_waitcnt vmcnt(13)
	v_add_u32_e32 v17, v17, v1
	s_waitcnt vmcnt(12)
	v_add_u32_e32 v17, v17, v2
	s_waitcnt vmcnt(11)
	v_add_u32_e32 v17, v17, v3
	s_waitcnt vmcnt(10)
	v_add_u32_e32 v17, v17, v4
	s_waitcnt vmcnt(9)
	v_add_u32_e32 v17, v17, v5
	s_waitcnt vmcnt(8)
	v_add_u32_e32 v17, v17, v6
	s_waitcnt vmcnt(7)
	v_add_u32_e32 v17, v17, v7
	s_waitcnt vmcnt(6)
	v_add_u32_e32 v17, v17, v8
	s_waitcnt vmcnt(5)
	v_add_u32_e32 v17, v17, v9
	s_waitcnt vmcnt(4)
	v_add_u32_e32 v17, v17, v10
	s_waitcnt vmcnt(3)
	v_add_u32_e32 v17, v17, v11
	s_waitcnt vmcnt(2)
	v_add_u32_e32 v17, v17, v12
	s_waitcnt vmcnt(1)
	v_add_u32_e32 v17, v17, v13
	s_waitcnt vmcnt(0)
	v_add_u32_e32 v17, v17, v14
	v_cmp_eq_u32_e32 vcc, s84, v17
	s_cbranch_vccnz .LBB0_231
	s_and_b32 s20, s85, 0xff
	s_cmp_eq_u32 s20, 0
	s_mov_b64 s[20:21], -1
	s_mov_b64 s[68:69], -1
	s_cbranch_scc0 .LBB0_236
	global_load_dword v17, v16, s[4:5] sc1
	s_waitcnt vmcnt(0)
	v_cmp_eq_u32_e32 vcc, 0, v17
	s_cbranch_vccnz .LBB0_238
	s_mov_b64 s[68:69], 0

.LBB0_250:
	s_and_b32 s23, s58, 0xff
	s_mov_b64 s[20:21], -1
	s_cmp_lg_u32 s23, 0
	s_mov_b64 s[56:57], -1
	s_cbranch_scc1 .LBB0_253
	global_load_dword v2, v0, s[10:11] sc1
	s_waitcnt vmcnt(0)
	v_cmp_eq_u32_e32 vcc, 0, v2
	s_cbranch_vccnz .LBB0_255
	s_mov_b64 s[56:57], 0
	s_mov_b64 s[54:55], -1

.LBB0_267:
	s_and_b32 s20, s58, 0xff
	s_cmp_lg_u32 s20, 0
	s_mov_b64 s[54:55], -1
	s_cbranch_scc1 .LBB0_270
	global_load_dword v1, v0, s[10:11] sc1
	s_waitcnt vmcnt(0)
	v_cmp_eq_u32_e32 vcc, 0, v1
	s_cbranch_vccnz .LBB0_272
	s_mov_b64 s[54:55], 0
	s_mov_b64 s[20:21], -1

.LBB0_310:
	global_load_dword v15, v16, s[6:7] sc1
	s_waitcnt lgkmcnt(0)
	global_load_dword v0, v16, s[8:9] sc1
	global_load_dword v1, v16, s[10:11] sc1
	global_load_dword v2, v16, s[12:13] sc1
	global_load_dword v3, v16, s[14:15] sc1
	global_load_dword v4, v16, s[16:17] sc1
	global_load_dword v5, v16, s[18:19] sc1
	global_load_dword v6, v16, s[54:55] sc1
	global_load_dword v7, v16, s[56:57] sc1
	global_load_dword v8, v16, s[58:59] sc1
	global_load_dword v9, v16, s[64:65] sc1
	global_load_dword v10, v16, s[70:71] sc1
	global_load_dword v11, v16, s[72:73] sc1
	global_load_dword v12, v16, s[74:75] sc1
	global_load_dword v13, v16, s[76:77] sc1
	global_load_dword v14, v16, s[78:79] sc1
	s_mov_b64 s[20:21], -1
	s_mov_b64 s[80:81], -1
	s_waitcnt vmcnt(14)
	v_add_u32_e32 v17, v0, v15
	s_waitcnt vmcnt(13)
	v_add_u32_e32 v17, v17, v1
	s_waitcnt vmcnt(12)
	v_add_u32_e32 v17, v17, v2
	s_waitcnt vmcnt(11)
	v_add_u32_e32 v17, v17, v3
	s_waitcnt vmcnt(10)
	v_add_u32_e32 v17, v17, v4
	s_waitcnt vmcnt(9)
	v_add_u32_e32 v17, v17, v5
	s_waitcnt vmcnt(8)
	v_add_u32_e32 v17, v17, v6
	s_waitcnt vmcnt(7)
	v_add_u32_e32 v17, v17, v7
	s_waitcnt vmcnt(6)
	v_add_u32_e32 v17, v17, v8
	s_waitcnt vmcnt(5)
	v_add_u32_e32 v17, v17, v9
	s_waitcnt vmcnt(4)
	v_add_u32_e32 v17, v17, v10
	s_waitcnt vmcnt(3)
	v_add_u32_e32 v17, v17, v11
	s_waitcnt vmcnt(2)
	v_add_u32_e32 v17, v17, v12
	s_waitcnt vmcnt(1)
	v_add_u32_e32 v17, v17, v13
	s_waitcnt vmcnt(0)
	v_add_u32_e32 v17, v17, v14
	v_cmp_eq_u32_e32 vcc, s82, v17
	s_cbranch_vccnz .LBB0_309
	s_and_b32 s20, s83, 0xff
	s_cmp_eq_u32 s20, 0
	s_mov_b64 s[20:21], -1
	s_mov_b64 s[68:69], -1
	s_cbranch_scc0 .LBB0_314
	global_load_dword v17, v16, s[4:5] sc1
	s_waitcnt vmcnt(0)
	v_cmp_eq_u32_e32 vcc, 0, v17
	s_cbranch_vccnz .LBB0_316
	s_mov_b64 s[68:69], 0

.LBB0_328:
	s_and_b32 s20, s56, 0xff
	s_mov_b64 s[18:19], -1
	s_cmp_lg_u32 s20, 0
	s_mov_b64 s[54:55], -1
	s_cbranch_scc1 .LBB0_331
	global_load_dword v2, v0, s[10:11] sc1
	s_waitcnt vmcnt(0)
	v_cmp_eq_u32_e32 vcc, 0, v2
	s_cbranch_vccnz .LBB0_333
	s_mov_b64 s[54:55], 0
	s_mov_b64 s[20:21], -1

.LBB0_345:
	s_and_b32 s18, s56, 0xff
	s_cmp_lg_u32 s18, 0
	s_mov_b64 s[20:21], -1
	s_cbranch_scc1 .LBB0_348
	global_load_dword v1, v0, s[10:11] sc1
	s_waitcnt vmcnt(0)
	v_cmp_eq_u32_e32 vcc, 0, v1
	s_cbranch_vccnz .LBB0_350
	s_mov_b64 s[20:21], 0
	s_mov_b64 s[18:19], -1

.LBB0_641:
	global_load_dword v15, v16, s[6:7] sc1
	s_waitcnt lgkmcnt(0)
	global_load_dword v0, v16, s[8:9] sc1
	global_load_dword v1, v16, s[10:11] sc1
	global_load_dword v2, v16, s[12:13] sc1
	global_load_dword v3, v16, s[14:15] sc1
	global_load_dword v4, v16, s[16:17] sc1
	global_load_dword v5, v16, s[18:19] sc1
	global_load_dword v6, v16, s[44:45] sc1
	global_load_dword v7, v16, s[46:47] sc1
	global_load_dword v8, v16, s[48:49] sc1
	global_load_dword v9, v16, s[50:51] sc1
	global_load_dword v10, v16, s[52:53] sc1
	global_load_dword v11, v16, s[54:55] sc1
	global_load_dword v12, v16, s[56:57] sc1
	global_load_dword v13, v16, s[58:59] sc1
	global_load_dword v14, v16, s[64:65] sc1
	s_mov_b64 s[20:21], -1
	s_mov_b64 s[70:71], -1
	s_waitcnt vmcnt(14)
	v_add_u32_e32 v17, v0, v15
	s_waitcnt vmcnt(13)
	v_add_u32_e32 v17, v17, v1
	s_waitcnt vmcnt(12)
	v_add_u32_e32 v17, v17, v2
	s_waitcnt vmcnt(11)
	v_add_u32_e32 v17, v17, v3
	s_waitcnt vmcnt(10)
	v_add_u32_e32 v17, v17, v4
	s_waitcnt vmcnt(9)
	v_add_u32_e32 v17, v17, v5
	s_waitcnt vmcnt(8)
	v_add_u32_e32 v17, v17, v6
	s_waitcnt vmcnt(7)
	v_add_u32_e32 v17, v17, v7
	s_waitcnt vmcnt(6)
	v_add_u32_e32 v17, v17, v8
	s_waitcnt vmcnt(5)
	v_add_u32_e32 v17, v17, v9
	s_waitcnt vmcnt(4)
	v_add_u32_e32 v17, v17, v10
	s_waitcnt vmcnt(3)
	v_add_u32_e32 v17, v17, v11
	s_waitcnt vmcnt(2)
	v_add_u32_e32 v17, v17, v12
	s_waitcnt vmcnt(1)
	v_add_u32_e32 v17, v17, v13
	s_waitcnt vmcnt(0)
	v_add_u32_e32 v17, v17, v14
	v_cmp_eq_u32_e32 vcc, s72, v17
	s_cbranch_vccnz .LBB0_640
	s_and_b32 s20, s73, 0xff
	s_cmp_eq_u32 s20, 0
	s_mov_b64 s[20:21], -1
	s_mov_b64 s[68:69], -1
	s_cbranch_scc0 .LBB0_645
	global_load_dword v17, v16, s[4:5] sc1
	s_waitcnt vmcnt(0)
	v_cmp_eq_u32_e32 vcc, 0, v17
	s_cbranch_vccnz .LBB0_647
	s_mov_b64 s[68:69], 0

.LBB0_659:
	s_and_b32 s20, s46, 0xff
	s_mov_b64 s[18:19], -1
	s_cmp_lg_u32 s20, 0
	s_mov_b64 s[44:45], -1
	s_cbranch_scc1 .LBB0_662
	global_load_dword v2, v0, s[10:11] sc1
	s_waitcnt vmcnt(0)
	v_cmp_eq_u32_e32 vcc, 0, v2
	s_cbranch_vccnz .LBB0_664
	s_mov_b64 s[44:45], 0
	s_mov_b64 s[20:21], -1

.LBB0_676:
	s_and_b32 s18, s46, 0xff
	s_cmp_lg_u32 s18, 0
	s_mov_b64 s[20:21], -1
	s_cbranch_scc1 .LBB0_679
	global_load_dword v1, v0, s[10:11] sc1
	s_waitcnt vmcnt(0)
	v_cmp_eq_u32_e32 vcc, 0, v1
	s_cbranch_vccnz .LBB0_681
	s_mov_b64 s[20:21], 0
	s_mov_b64 s[18:19], -1

.LBB0_925:
	global_load_dword v15, v16, s[6:7] sc1
	s_waitcnt lgkmcnt(0)
	global_load_dword v0, v16, s[8:9] sc1
	global_load_dword v1, v16, s[10:11] sc1
	global_load_dword v2, v16, s[12:13] sc1
	global_load_dword v3, v16, s[14:15] sc1
	global_load_dword v4, v16, s[16:17] sc1
	global_load_dword v5, v16, s[18:19] sc1
	global_load_dword v6, v16, s[44:45] sc1
	global_load_dword v7, v16, s[46:47] sc1
	global_load_dword v8, v16, s[48:49] sc1
	global_load_dword v9, v16, s[50:51] sc1
	global_load_dword v10, v16, s[52:53] sc1
	global_load_dword v11, v16, s[54:55] sc1
	global_load_dword v12, v16, s[56:57] sc1
	global_load_dword v13, v16, s[58:59] sc1
	global_load_dword v14, v16, s[60:61] sc1
	s_mov_b64 s[20:21], -1
	s_mov_b64 s[62:63], -1
	s_waitcnt vmcnt(14)
	v_add_u32_e32 v17, v0, v15
	s_waitcnt vmcnt(13)
	v_add_u32_e32 v17, v17, v1
	s_waitcnt vmcnt(12)
	v_add_u32_e32 v17, v17, v2
	s_waitcnt vmcnt(11)
	v_add_u32_e32 v17, v17, v3
	s_waitcnt vmcnt(10)
	v_add_u32_e32 v17, v17, v4
	s_waitcnt vmcnt(9)
	v_add_u32_e32 v17, v17, v5
	s_waitcnt vmcnt(8)
	v_add_u32_e32 v17, v17, v6
	s_waitcnt vmcnt(7)
	v_add_u32_e32 v17, v17, v7
	s_waitcnt vmcnt(6)
	v_add_u32_e32 v17, v17, v8
	s_waitcnt vmcnt(5)
	v_add_u32_e32 v17, v17, v9
	s_waitcnt vmcnt(4)
	v_add_u32_e32 v17, v17, v10
	s_waitcnt vmcnt(3)
	v_add_u32_e32 v17, v17, v11
	s_waitcnt vmcnt(2)
	v_add_u32_e32 v17, v17, v12
	s_waitcnt vmcnt(1)
	v_add_u32_e32 v17, v17, v13
	s_waitcnt vmcnt(0)
	v_add_u32_e32 v17, v17, v14
	v_cmp_eq_u32_e32 vcc, s66, v17
	s_cbranch_vccnz .LBB0_924
	s_and_b32 s20, s67, 0xff
	s_cmp_eq_u32 s20, 0
	s_mov_b64 s[20:21], -1
	s_mov_b64 s[64:65], -1
	s_cbranch_scc0 .LBB0_929
	global_load_dword v17, v16, s[4:5] sc1
	s_waitcnt vmcnt(0)
	v_cmp_eq_u32_e32 vcc, 0, v17
	s_cbranch_vccnz .LBB0_931
	s_mov_b64 s[64:65], 0

.LBB0_1023:
	global_load_dword v15, v16, s[6:7] sc1
	s_waitcnt lgkmcnt(0)
	global_load_dword v0, v16, s[8:9] sc1
	global_load_dword v1, v16, s[10:11] sc1
	global_load_dword v2, v16, s[12:13] sc1
	global_load_dword v3, v16, s[14:15] sc1
	global_load_dword v4, v16, s[16:17] sc1
	global_load_dword v5, v16, s[18:19] sc1
	global_load_dword v6, v16, s[36:37] sc1
	global_load_dword v7, v16, s[38:39] sc1
	global_load_dword v8, v16, s[44:45] sc1
	global_load_dword v9, v16, s[46:47] sc1
	global_load_dword v10, v16, s[48:49] sc1
	global_load_dword v11, v16, s[50:51] sc1
	global_load_dword v12, v16, s[52:53] sc1
	global_load_dword v13, v16, s[54:55] sc1
	global_load_dword v14, v16, s[56:57] sc1
	s_mov_b64 s[20:21], -1
	s_mov_b64 s[58:59], -1
	s_waitcnt vmcnt(14)
	v_add_u32_e32 v17, v0, v15
	s_waitcnt vmcnt(13)
	v_add_u32_e32 v17, v17, v1
	s_waitcnt vmcnt(12)
	v_add_u32_e32 v17, v17, v2
	s_waitcnt vmcnt(11)
	v_add_u32_e32 v17, v17, v3
	s_waitcnt vmcnt(10)
	v_add_u32_e32 v17, v17, v4
	s_waitcnt vmcnt(9)
	v_add_u32_e32 v17, v17, v5
	s_waitcnt vmcnt(8)
	v_add_u32_e32 v17, v17, v6
	s_waitcnt vmcnt(7)
	v_add_u32_e32 v17, v17, v7
	s_waitcnt vmcnt(6)
	v_add_u32_e32 v17, v17, v8
	s_waitcnt vmcnt(5)
	v_add_u32_e32 v17, v17, v9
	s_waitcnt vmcnt(4)
	v_add_u32_e32 v17, v17, v10
	s_waitcnt vmcnt(3)
	v_add_u32_e32 v17, v17, v11
	s_waitcnt vmcnt(2)
	v_add_u32_e32 v17, v17, v12
	s_waitcnt vmcnt(1)
	v_add_u32_e32 v17, v17, v13
	s_waitcnt vmcnt(0)
	v_add_u32_e32 v17, v17, v14
	v_cmp_eq_u32_e32 vcc, s62, v17
	s_cbranch_vccnz .LBB0_1022
	s_and_b32 s20, s63, 0xff
	s_cmp_eq_u32 s20, 0
	s_mov_b64 s[20:21], -1
	s_mov_b64 s[60:61], -1
	s_cbranch_scc0 .LBB0_1027
	global_load_dword v17, v16, s[4:5] sc1
	s_waitcnt vmcnt(0)
	v_cmp_eq_u32_e32 vcc, 0, v17
	s_cbranch_vccnz .LBB0_1029
	s_mov_b64 s[60:61], 0

.LBB0_1041:
	s_and_b32 s20, s38, 0xff
	s_mov_b64 s[18:19], -1
	s_cmp_lg_u32 s20, 0
	s_mov_b64 s[36:37], -1
	s_cbranch_scc1 .LBB0_1044
	global_load_dword v2, v0, s[10:11] sc1
	s_waitcnt vmcnt(0)
	v_cmp_eq_u32_e32 vcc, 0, v2
	s_cbranch_vccnz .LBB0_1046
	s_mov_b64 s[36:37], 0
	s_mov_b64 s[20:21], -1

.LBB0_1058:
	s_and_b32 s18, s38, 0xff
	s_cmp_lg_u32 s18, 0
	s_mov_b64 s[20:21], -1
	s_cbranch_scc1 .LBB0_1061
	global_load_dword v1, v0, s[10:11] sc1
	s_waitcnt vmcnt(0)
	v_cmp_eq_u32_e32 vcc, 0, v1
	s_cbranch_vccnz .LBB0_1063
	s_mov_b64 s[20:21], 0
	s_mov_b64 s[18:19], -1

.LBB0_1181:
	global_load_dword v15, v16, s[6:7] sc1
	s_waitcnt lgkmcnt(0)
	global_load_dword v0, v16, s[8:9] sc1
	global_load_dword v1, v16, s[10:11] sc1
	global_load_dword v2, v16, s[12:13] sc1
	global_load_dword v3, v16, s[14:15] sc1
	global_load_dword v4, v16, s[16:17] sc1
	global_load_dword v5, v16, s[18:19] sc1
	global_load_dword v6, v16, s[36:37] sc1
	global_load_dword v7, v16, s[38:39] sc1
	global_load_dword v8, v16, s[40:41] sc1
	global_load_dword v9, v16, s[42:43] sc1
	global_load_dword v10, v16, s[44:45] sc1
	global_load_dword v11, v16, s[46:47] sc1
	global_load_dword v12, v16, s[48:49] sc1
	global_load_dword v13, v16, s[50:51] sc1
	global_load_dword v14, v16, s[52:53] sc1
	s_mov_b64 s[20:21], -1
	s_mov_b64 s[54:55], -1
	s_waitcnt vmcnt(14)
	v_add_u32_e32 v17, v0, v15
	s_waitcnt vmcnt(13)
	v_add_u32_e32 v17, v17, v1
	s_waitcnt vmcnt(12)
	v_add_u32_e32 v17, v17, v2
	s_waitcnt vmcnt(11)
	v_add_u32_e32 v17, v17, v3
	s_waitcnt vmcnt(10)
	v_add_u32_e32 v17, v17, v4
	s_waitcnt vmcnt(9)
	v_add_u32_e32 v17, v17, v5
	s_waitcnt vmcnt(8)
	v_add_u32_e32 v17, v17, v6
	s_waitcnt vmcnt(7)
	v_add_u32_e32 v17, v17, v7
	s_waitcnt vmcnt(6)
	v_add_u32_e32 v17, v17, v8
	s_waitcnt vmcnt(5)
	v_add_u32_e32 v17, v17, v9
	s_waitcnt vmcnt(4)
	v_add_u32_e32 v17, v17, v10
	s_waitcnt vmcnt(3)
	v_add_u32_e32 v17, v17, v11
	s_waitcnt vmcnt(2)
	v_add_u32_e32 v17, v17, v12
	s_waitcnt vmcnt(1)
	v_add_u32_e32 v17, v17, v13
	s_waitcnt vmcnt(0)
	v_add_u32_e32 v17, v17, v14
	v_cmp_eq_u32_e32 vcc, s58, v17
	s_cbranch_vccnz .LBB0_1180
	s_and_b32 s20, s59, 0xff
	s_cmp_eq_u32 s20, 0
	s_mov_b64 s[20:21], -1
	s_mov_b64 s[56:57], -1
	s_cbranch_scc0 .LBB0_1185
	global_load_dword v17, v16, s[4:5] sc1
	s_waitcnt vmcnt(0)
	v_cmp_eq_u32_e32 vcc, 0, v17
	s_cbranch_vccnz .LBB0_1187
	s_mov_b64 s[56:57], 0

.LBB0_1460:
	global_load_dword v15, v16, s[6:7] sc1
	s_waitcnt lgkmcnt(0)
	global_load_dword v0, v16, s[8:9] sc1
	global_load_dword v1, v16, s[10:11] sc1
	global_load_dword v2, v16, s[12:13] sc1
	global_load_dword v3, v16, s[14:15] sc1
	global_load_dword v4, v16, s[16:17] sc1
	global_load_dword v5, v16, s[18:19] sc1
	global_load_dword v6, v16, s[20:21] sc1
	global_load_dword v7, v16, s[36:37] sc1
	global_load_dword v8, v16, s[38:39] sc1
	global_load_dword v9, v16, s[40:41] sc1
	global_load_dword v10, v16, s[42:43] sc1
	global_load_dword v11, v16, s[44:45] sc1
	global_load_dword v12, v16, s[46:47] sc1
	global_load_dword v13, v16, s[48:49] sc1
	global_load_dword v14, v16, s[50:51] sc1
	s_mov_b64 s[52:53], -1
	s_mov_b64 s[54:55], -1
	s_waitcnt vmcnt(14)
	v_add_u32_e32 v17, v0, v15
	s_waitcnt vmcnt(13)
	v_add_u32_e32 v17, v17, v1
	s_waitcnt vmcnt(12)
	v_add_u32_e32 v17, v17, v2
	s_waitcnt vmcnt(11)
	v_add_u32_e32 v17, v17, v3
	s_waitcnt vmcnt(10)
	v_add_u32_e32 v17, v17, v4
	s_waitcnt vmcnt(9)
	v_add_u32_e32 v17, v17, v5
	s_waitcnt vmcnt(8)
	v_add_u32_e32 v17, v17, v6
	s_waitcnt vmcnt(7)
	v_add_u32_e32 v17, v17, v7
	s_waitcnt vmcnt(6)
	v_add_u32_e32 v17, v17, v8
	s_waitcnt vmcnt(5)
	v_add_u32_e32 v17, v17, v9
	s_waitcnt vmcnt(4)
	v_add_u32_e32 v17, v17, v10
	s_waitcnt vmcnt(3)
	v_add_u32_e32 v17, v17, v11
	s_waitcnt vmcnt(2)
	v_add_u32_e32 v17, v17, v12
	s_waitcnt vmcnt(1)
	v_add_u32_e32 v17, v17, v13
	s_waitcnt vmcnt(0)
	v_add_u32_e32 v17, v17, v14
	v_cmp_eq_u32_e32 vcc, s31, v17
	s_cbranch_vccnz .LBB0_1459
	s_and_b32 s23, s33, 0xff
	s_cmp_eq_u32 s23, 0
	s_mov_b64 s[56:57], -1
	s_cbranch_scc0 .LBB0_1464
	global_load_dword v17, v16, s[4:5] sc1
	s_waitcnt vmcnt(0)
	v_cmp_eq_u32_e32 vcc, 0, v17
	s_cbranch_vccnz .LBB0_1466
	s_mov_b64 s[56:57], 0

.LBB0_1478:
	s_and_b32 s20, s23, 0xff
	s_mov_b64 s[18:19], -1
	s_cmp_lg_u32 s20, 0
	s_mov_b64 s[36:37], -1
	s_cbranch_scc1 .LBB0_1481
	global_load_dword v2, v0, s[10:11] sc1
	s_waitcnt vmcnt(0)
	v_cmp_eq_u32_e32 vcc, 0, v2
	s_cbranch_vccnz .LBB0_1483
	s_mov_b64 s[36:37], 0
	s_mov_b64 s[20:21], -1

.LBB0_1495:
	s_and_b32 s18, s23, 0xff
	s_cmp_lg_u32 s18, 0
	s_mov_b64 s[20:21], -1
	s_cbranch_scc1 .LBB0_1498
	global_load_dword v1, v0, s[10:11] sc1
	s_waitcnt vmcnt(0)
	v_cmp_eq_u32_e32 vcc, 0, v1
	s_cbranch_vccnz .LBB0_1500
	s_mov_b64 s[20:21], 0
	s_mov_b64 s[18:19], -1
